# phase 3: second-layer weight block staged by LDS-DMA (direct HBM->LDS, lever 5) instead of load / wait ladder / ds_write
# speedup vs baseline: 1.0013x; 1.0013x over previous
; #define LAS __attribute__((address_space(3)))
; __device__ __forceinline__ void phase3(const Args& a, LAS unsigned char* lds) {
;     ...
;     for (int item = blockIdx.x; item < nchunk; item += gridDim.x) {
;         const int kv = (item * 32) >> 12;
;         __syncthreads();
;         { const f32x4* src = (const f32x4*)(a.in[7] + (size_t)kv * 256 * 64);
; #pragma unroll
;           for (int i = 0; i < 8; ++i) ((LAS f32x4*)w2s)[tid + 512 * i] = src[tid + 512 * i]; }
;         if (tid < 256) { float t = 0.f;
; #pragma unroll
;             for (int kch = 0; kch < 64; ++kch) t += c1p[kch * 512 + kv * 256 + tid];
;             c1s[tid] = t; }
.LBB0_589:
	s_ashr_i32 s4, s20, 7
	s_ashr_i32 s5, s4, 31
	s_lshl_b64 s[0:1], s[4:5], 16
	s_add_u32 s0, s86, s0
	s_addc_u32 s1, s87, s1
	v_lshl_add_u64 v[10:11], s[0:1], 0, v[8:9]
	v_add_co_u32_e32 v36, vcc, s14, v10
	s_waitcnt vmcnt(0) lgkmcnt(0)
	s_nop 0
	v_addc_co_u32_e32 v37, vcc, 0, v11, vcc
	v_add_co_u32_e32 v44, vcc, s15, v10
	s_barrier
	v_lshl_add_u32 v168, s20, 5, v13
	v_mov_b32_e32 v169, 0
	v_lshlrev_b64 v[168:169], 10, v[168:169]
	v_lshl_add_u64 v[168:169], v[4:5], 0, v[168:169]
	s_mov_b32 s6, 0x800000
	s_mov_b32 s7, 0
	v_lshl_add_u64 v[170:171], v[168:169], 0, s[6:7]
	v_lshl_add_u64 v[172:173], v[170:171], 0, s[6:7]
	v_lshl_add_u64 v[174:175], v[172:173], 0, s[6:7]
	global_load_dwordx4 v[100:103], v[168:169], off
	global_load_dwordx4 v[104:107], v[170:171], off
	global_load_dwordx4 v[108:111], v[172:173], off
	global_load_dwordx4 v[112:115], v[174:175], off
	global_load_dwordx4 v[116:119], v[168:169], off offset:1024
	global_load_dwordx4 v[120:123], v[170:171], off offset:1024
	global_load_dwordx4 v[124:127], v[172:173], off offset:1024
	global_load_dwordx4 v[128:131], v[174:175], off offset:1024
	global_load_dwordx4 v[132:135], v[168:169], off offset:2048
	global_load_dwordx4 v[136:139], v[170:171], off offset:2048
	global_load_dwordx4 v[140:143], v[172:173], off offset:2048
	global_load_dwordx4 v[144:147], v[174:175], off offset:2048
	global_load_dwordx4 v[152:155], v[168:169], off offset:3072
	global_load_dwordx4 v[156:159], v[170:171], off offset:3072
	global_load_dwordx4 v[160:163], v[172:173], off offset:3072
	global_load_dwordx4 v[164:167], v[174:175], off offset:3072
	global_load_dword v176, v[6:7], off
	v_readfirstlane_b32 s30, v149
	s_mov_b32 s28, s0
	s_mov_b32 s29, s1
	s_lshl_b32 s30, s30, 10
	s_mov_b32 m0, s30
	s_nop 0
	global_load_lds_dwordx4 v8, s[28:29]
	s_add_u32 s28, s28, 0x2000
	s_addc_u32 s29, s29, 0
	s_add_i32 m0, s30, 0x2000
	s_nop 0
	global_load_lds_dwordx4 v8, s[28:29]
	s_add_u32 s28, s28, 0x2000
	s_addc_u32 s29, s29, 0
	s_add_i32 m0, s30, 0x4000
	s_nop 0
	global_load_lds_dwordx4 v8, s[28:29]
	s_add_u32 s28, s28, 0x2000
	s_addc_u32 s29, s29, 0
	s_add_i32 m0, s30, 0x6000
	s_nop 0
	global_load_lds_dwordx4 v8, s[28:29]
	s_add_u32 s28, s28, 0x2000
	s_addc_u32 s29, s29, 0
	s_add_i32 m0, s30, 0x8000
	s_nop 0
	global_load_lds_dwordx4 v8, s[28:29]
	s_add_u32 s28, s28, 0x2000
	s_addc_u32 s29, s29, 0
	s_add_i32 m0, s30, 0xa000
	s_nop 0
	global_load_lds_dwordx4 v8, s[28:29]
	s_add_u32 s28, s28, 0x2000
	s_addc_u32 s29, s29, 0
	s_add_i32 m0, s30, 0xc000
	s_nop 0
	global_load_lds_dwordx4 v8, s[28:29]
	s_add_u32 s28, s28, 0x2000
	s_addc_u32 s29, s29, 0
	s_add_i32 m0, s30, 0xe000
	s_nop 0
	global_load_lds_dwordx4 v8, s[28:29]
	s_and_saveexec_b64 s[0:1], s[2:3]
	s_cbranch_execz .LBB0_591
	v_lshl_or_b32 v10, s4, 8, v184
	v_add_u32_e32 v24, 0x200, v10
	v_ashrrev_i32_e32 v25, 31, v24
	v_lshl_add_u64 v[32:33], v[24:25], 2, s[10:11]
	v_add_u32_e32 v24, 0x400, v10
	v_ashrrev_i32_e32 v25, 31, v24
	v_lshl_add_u64 v[34:35], v[24:25], 2, s[10:11]
	v_add_u32_e32 v24, 0x600, v10
	v_ashrrev_i32_e32 v25, 31, v24
	v_lshl_add_u64 v[36:37], v[24:25], 2, s[10:11]
	v_add_u32_e32 v24, 0x800, v10
	v_ashrrev_i32_e32 v25, 31, v24
	v_lshl_add_u64 v[38:39], v[24:25], 2, s[10:11]
	v_add_u32_e32 v24, 0xa00, v10
	v_ashrrev_i32_e32 v25, 31, v24
	v_lshl_add_u64 v[40:41], v[24:25], 2, s[10:11]
	v_add_u32_e32 v24, 0xc00, v10
	v_ashrrev_i32_e32 v25, 31, v24
	v_ashrrev_i32_e32 v11, 31, v10
	v_lshl_add_u64 v[42:43], v[24:25], 2, s[10:11]
	v_add_u32_e32 v24, 0xe00, v10
	v_lshl_add_u64 v[30:31], v[10:11], 2, s[10:11]
	v_ashrrev_i32_e32 v25, 31, v24
	v_lshl_add_u64 v[44:45], v[24:25], 2, s[10:11]
	global_load_dword v2, v[30:31], off
	global_load_dword v11, v[32:33], off
	global_load_dword v23, v[34:35], off
	global_load_dword v24, v[36:37], off
	global_load_dword v25, v[38:39], off
	global_load_dword v26, v[40:41], off
	global_load_dword v27, v[42:43], off
	global_load_dword v28, v[44:45], off
	v_add_u32_e32 v30, 0x1000, v10
	v_ashrrev_i32_e32 v31, 31, v30
	v_add_u32_e32 v32, 0x1200, v10
	v_add_u32_e32 v34, 0x1400, v10
	v_add_u32_e32 v36, 0x1600, v10
	v_add_u32_e32 v38, 0x1800, v10
	v_add_u32_e32 v40, 0x1a00, v10
	v_add_u32_e32 v42, 0x1c00, v10
	v_add_u32_e32 v44, 0x1e00, v10
	v_lshl_add_u64 v[30:31], v[30:31], 2, s[10:11]
	v_ashrrev_i32_e32 v33, 31, v32
	v_ashrrev_i32_e32 v35, 31, v34
	v_ashrrev_i32_e32 v37, 31, v36
	v_ashrrev_i32_e32 v39, 31, v38
	v_ashrrev_i32_e32 v41, 31, v40
	v_ashrrev_i32_e32 v43, 31, v42
	v_ashrrev_i32_e32 v45, 31, v44
	v_lshl_add_u64 v[32:33], v[32:33], 2, s[10:11]
	v_lshl_add_u64 v[34:35], v[34:35], 2, s[10:11]
	v_lshl_add_u64 v[36:37], v[36:37], 2, s[10:11]
	v_lshl_add_u64 v[38:39], v[38:39], 2, s[10:11]
	v_lshl_add_u64 v[40:41], v[40:41], 2, s[10:11]
	v_lshl_add_u64 v[42:43], v[42:43], 2, s[10:11]
	v_lshl_add_u64 v[44:45], v[44:45], 2, s[10:11]
	global_load_dword v29, v[30:31], off
	global_load_dword v46, v[32:33], off
	global_load_dword v47, v[34:35], off
	global_load_dword v48, v[36:37], off
	global_load_dword v49, v[38:39], off
	global_load_dword v50, v[40:41], off
	global_load_dword v51, v[42:43], off
	global_load_dword v52, v[44:45], off
	v_add_u32_e32 v30, 0x2000, v10
	v_ashrrev_i32_e32 v31, 31, v30
	v_add_u32_e32 v32, 0x2200, v10
	v_add_u32_e32 v34, 0x2400, v10
	v_add_u32_e32 v36, 0x2600, v10
	v_add_u32_e32 v38, 0x2800, v10
	v_add_u32_e32 v40, 0x2a00, v10
	v_add_u32_e32 v42, 0x2c00, v10
	v_add_u32_e32 v44, 0x2e00, v10
	v_lshl_add_u64 v[30:31], v[30:31], 2, s[10:11]
	v_ashrrev_i32_e32 v33, 31, v32
	v_ashrrev_i32_e32 v35, 31, v34
	v_ashrrev_i32_e32 v37, 31, v36
	v_ashrrev_i32_e32 v39, 31, v38
	v_ashrrev_i32_e32 v41, 31, v40
; __device__ __forceinline__ void phase3(const Args& a, LAS unsigned char* lds) {
;     ...
;         if (tid < 256) { float t = 0.f;
; #pragma unroll
;             for (int kch = 0; kch < 64; ++kch) t += c1p[kch * 512 + kv * 256 + tid];
	v_ashrrev_i32_e32 v43, 31, v42
	v_ashrrev_i32_e32 v45, 31, v44
	v_lshl_add_u64 v[32:33], v[32:33], 2, s[10:11]
	v_lshl_add_u64 v[34:35], v[34:35], 2, s[10:11]
	v_lshl_add_u64 v[36:37], v[36:37], 2, s[10:11]
	v_lshl_add_u64 v[38:39], v[38:39], 2, s[10:11]
	v_lshl_add_u64 v[40:41], v[40:41], 2, s[10:11]
	v_lshl_add_u64 v[42:43], v[42:43], 2, s[10:11]
	v_lshl_add_u64 v[44:45], v[44:45], 2, s[10:11]
	global_load_dword v53, v[30:31], off
	global_load_dword v54, v[32:33], off
	global_load_dword v55, v[34:35], off
	global_load_dword v56, v[36:37], off
	global_load_dword v57, v[38:39], off
	global_load_dword v58, v[40:41], off
	global_load_dword v59, v[42:43], off
	global_load_dword v60, v[44:45], off
	v_add_u32_e32 v30, 0x3000, v10
	v_ashrrev_i32_e32 v31, 31, v30
	v_add_u32_e32 v32, 0x3200, v10
	v_add_u32_e32 v34, 0x3400, v10
	v_add_u32_e32 v36, 0x3600, v10
	v_add_u32_e32 v38, 0x3800, v10
	v_add_u32_e32 v40, 0x3a00, v10
	v_add_u32_e32 v42, 0x3c00, v10
	v_add_u32_e32 v44, 0x3e00, v10
	v_lshl_add_u64 v[30:31], v[30:31], 2, s[10:11]
	v_ashrrev_i32_e32 v33, 31, v32
	v_ashrrev_i32_e32 v35, 31, v34
	v_ashrrev_i32_e32 v37, 31, v36
	v_ashrrev_i32_e32 v39, 31, v38
	v_ashrrev_i32_e32 v41, 31, v40
	v_ashrrev_i32_e32 v43, 31, v42
	v_ashrrev_i32_e32 v45, 31, v44
	v_lshl_add_u64 v[32:33], v[32:33], 2, s[10:11]
	v_lshl_add_u64 v[34:35], v[34:35], 2, s[10:11]
	v_lshl_add_u64 v[36:37], v[36:37], 2, s[10:11]
	v_lshl_add_u64 v[38:39], v[38:39], 2, s[10:11]
	v_lshl_add_u64 v[40:41], v[40:41], 2, s[10:11]
	v_lshl_add_u64 v[42:43], v[42:43], 2, s[10:11]
	v_lshl_add_u64 v[44:45], v[44:45], 2, s[10:11]
	global_load_dword v61, v[30:31], off
	global_load_dword v62, v[32:33], off
	global_load_dword v63, v[34:35], off
	global_load_dword v64, v[36:37], off
	global_load_dword v65, v[38:39], off
	global_load_dword v66, v[40:41], off
	global_load_dword v67, v[42:43], off
	global_load_dword v68, v[44:45], off
	v_add_u32_e32 v30, 0x4000, v10
	v_ashrrev_i32_e32 v31, 31, v30
	v_add_u32_e32 v32, 0x4200, v10
	v_add_u32_e32 v34, 0x4400, v10
	v_add_u32_e32 v36, 0x4600, v10
	v_add_u32_e32 v38, 0x4800, v10
	v_add_u32_e32 v40, 0x4a00, v10
	v_add_u32_e32 v42, 0x4c00, v10
	v_add_u32_e32 v44, 0x4e00, v10
	v_lshl_add_u64 v[30:31], v[30:31], 2, s[10:11]
	v_ashrrev_i32_e32 v33, 31, v32
	v_ashrrev_i32_e32 v35, 31, v34
	v_ashrrev_i32_e32 v37, 31, v36
	v_ashrrev_i32_e32 v39, 31, v38
	v_ashrrev_i32_e32 v41, 31, v40
	v_ashrrev_i32_e32 v43, 31, v42
	v_ashrrev_i32_e32 v45, 31, v44
	v_lshl_add_u64 v[32:33], v[32:33], 2, s[10:11]
	v_lshl_add_u64 v[34:35], v[34:35], 2, s[10:11]
	v_lshl_add_u64 v[36:37], v[36:37], 2, s[10:11]
	v_lshl_add_u64 v[38:39], v[38:39], 2, s[10:11]
	v_lshl_add_u64 v[40:41], v[40:41], 2, s[10:11]
	v_lshl_add_u64 v[42:43], v[42:43], 2, s[10:11]
	v_lshl_add_u64 v[44:45], v[44:45], 2, s[10:11]
	global_load_dword v69, v[30:31], off
	global_load_dword v70, v[32:33], off
	global_load_dword v71, v[34:35], off
	global_load_dword v72, v[36:37], off
	global_load_dword v73, v[38:39], off
	global_load_dword v74, v[40:41], off
	global_load_dword v75, v[42:43], off
	global_load_dword v76, v[44:45], off
	v_add_u32_e32 v30, 0x5000, v10
	v_ashrrev_i32_e32 v31, 31, v30
	v_add_u32_e32 v32, 0x5200, v10
	v_add_u32_e32 v34, 0x5400, v10
	v_add_u32_e32 v36, 0x5600, v10
	v_add_u32_e32 v38, 0x5800, v10
	v_add_u32_e32 v40, 0x5a00, v10
	v_add_u32_e32 v42, 0x5c00, v10
	v_add_u32_e32 v44, 0x5e00, v10
	v_lshl_add_u64 v[30:31], v[30:31], 2, s[10:11]
	v_ashrrev_i32_e32 v33, 31, v32
	v_ashrrev_i32_e32 v35, 31, v34
	v_ashrrev_i32_e32 v37, 31, v36
	v_ashrrev_i32_e32 v39, 31, v38
	v_ashrrev_i32_e32 v41, 31, v40
	v_ashrrev_i32_e32 v43, 31, v42
	v_ashrrev_i32_e32 v45, 31, v44
	v_lshl_add_u64 v[32:33], v[32:33], 2, s[10:11]
	v_lshl_add_u64 v[34:35], v[34:35], 2, s[10:11]
	v_lshl_add_u64 v[36:37], v[36:37], 2, s[10:11]
	v_lshl_add_u64 v[38:39], v[38:39], 2, s[10:11]
	v_lshl_add_u64 v[40:41], v[40:41], 2, s[10:11]
	v_lshl_add_u64 v[42:43], v[42:43], 2, s[10:11]
	v_lshl_add_u64 v[44:45], v[44:45], 2, s[10:11]
	global_load_dword v77, v[30:31], off
	global_load_dword v78, v[32:33], off
	global_load_dword v79, v[34:35], off
	global_load_dword v80, v[36:37], off
	global_load_dword v81, v[38:39], off
	global_load_dword v82, v[40:41], off
	global_load_dword v83, v[42:43], off
	global_load_dword v84, v[44:45], off
	v_add_u32_e32 v30, 0x6000, v10
	v_ashrrev_i32_e32 v31, 31, v30
	v_add_u32_e32 v32, 0x6200, v10
	v_add_u32_e32 v34, 0x6400, v10
	v_add_u32_e32 v36, 0x6600, v10
	v_add_u32_e32 v38, 0x6800, v10
	v_add_u32_e32 v40, 0x6a00, v10
	v_add_u32_e32 v42, 0x6c00, v10
	v_add_u32_e32 v44, 0x6e00, v10
	v_lshl_add_u64 v[30:31], v[30:31], 2, s[10:11]
	v_ashrrev_i32_e32 v33, 31, v32
	v_ashrrev_i32_e32 v35, 31, v34
	v_ashrrev_i32_e32 v37, 31, v36
	v_ashrrev_i32_e32 v39, 31, v38
	v_ashrrev_i32_e32 v41, 31, v40
	v_ashrrev_i32_e32 v43, 31, v42
	v_ashrrev_i32_e32 v45, 31, v44
	v_lshl_add_u64 v[32:33], v[32:33], 2, s[10:11]
	v_lshl_add_u64 v[34:35], v[34:35], 2, s[10:11]
	v_lshl_add_u64 v[36:37], v[36:37], 2, s[10:11]
	v_lshl_add_u64 v[38:39], v[38:39], 2, s[10:11]
	v_lshl_add_u64 v[40:41], v[40:41], 2, s[10:11]
	v_lshl_add_u64 v[42:43], v[42:43], 2, s[10:11]
	v_lshl_add_u64 v[44:45], v[44:45], 2, s[10:11]
	global_load_dword v85, v[30:31], off
	global_load_dword v86, v[32:33], off
	global_load_dword v87, v[34:35], off
	global_load_dword v88, v[36:37], off
	global_load_dword v89, v[38:39], off
	global_load_dword v90, v[40:41], off
	global_load_dword v91, v[42:43], off
	global_load_dword v92, v[44:45], off
	v_add_u32_e32 v30, 0x7000, v10
	v_ashrrev_i32_e32 v31, 31, v30
	v_add_u32_e32 v32, 0x7200, v10
	v_add_u32_e32 v34, 0x7400, v10
	v_add_u32_e32 v36, 0x7600, v10
	v_add_u32_e32 v38, 0x7800, v10
	v_add_u32_e32 v40, 0x7a00, v10
	v_add_u32_e32 v42, 0x7c00, v10
	v_add_u32_e32 v44, 0x7e00, v10
	v_lshl_add_u64 v[30:31], v[30:31], 2, s[10:11]
	v_ashrrev_i32_e32 v33, 31, v32
	v_ashrrev_i32_e32 v35, 31, v34
	v_ashrrev_i32_e32 v37, 31, v36
	v_ashrrev_i32_e32 v39, 31, v38
	v_ashrrev_i32_e32 v41, 31, v40
	v_ashrrev_i32_e32 v43, 31, v42
	v_ashrrev_i32_e32 v45, 31, v44
	v_lshl_add_u64 v[32:33], v[32:33], 2, s[10:11]
	v_lshl_add_u64 v[34:35], v[34:35], 2, s[10:11]
	v_lshl_add_u64 v[36:37], v[36:37], 2, s[10:11]
	v_lshl_add_u64 v[38:39], v[38:39], 2, s[10:11]
	v_lshl_add_u64 v[40:41], v[40:41], 2, s[10:11]
	v_lshl_add_u64 v[42:43], v[42:43], 2, s[10:11]
	v_lshl_add_u64 v[44:45], v[44:45], 2, s[10:11]
	global_load_dword v10, v[30:31], off
	global_load_dword v93, v[32:33], off
	global_load_dword v94, v[34:35], off
	global_load_dword v95, v[36:37], off
	global_load_dword v96, v[38:39], off
	global_load_dword v97, v[40:41], off
	global_load_dword v98, v[42:43], off
	global_load_dword v99, v[44:45], off
	s_waitcnt vmcnt(62)
; __device__ __forceinline__ void phase3(const Args& a, LAS unsigned char* lds) {
;     ...
;         if (tid < 256) { float t = 0.f;
; #pragma unroll
;             for (int kch = 0; kch < 64; ++kch) t += c1p[kch * 512 + kv * 256 + tid];
;             c1s[tid] = t; }
	v_add_f32_e32 v2, 0, v2
	v_add_f32_e32 v2, v2, v11
	s_waitcnt vmcnt(61)
	v_add_f32_e32 v2, v2, v23
	s_waitcnt vmcnt(60)
	v_add_f32_e32 v2, v2, v24
	s_waitcnt vmcnt(59)
	v_add_f32_e32 v2, v2, v25
	s_waitcnt vmcnt(58)
	v_add_f32_e32 v2, v2, v26
	s_waitcnt vmcnt(57)
	v_add_f32_e32 v2, v2, v27
	s_waitcnt vmcnt(56)
	v_add_f32_e32 v2, v2, v28
	s_waitcnt vmcnt(55)
	v_add_f32_e32 v2, v2, v29
	s_waitcnt vmcnt(54)
	v_add_f32_e32 v2, v2, v46
	s_waitcnt vmcnt(53)
	v_add_f32_e32 v2, v2, v47
	s_waitcnt vmcnt(52)
	v_add_f32_e32 v2, v2, v48
	s_waitcnt vmcnt(51)
	v_add_f32_e32 v2, v2, v49
	s_waitcnt vmcnt(50)
	v_add_f32_e32 v2, v2, v50
	s_waitcnt vmcnt(49)
	v_add_f32_e32 v2, v2, v51
	s_waitcnt vmcnt(48)
	v_add_f32_e32 v2, v2, v52
	s_waitcnt vmcnt(47)
	v_add_f32_e32 v2, v2, v53
	s_waitcnt vmcnt(46)
	v_add_f32_e32 v2, v2, v54
	s_waitcnt vmcnt(45)
	v_add_f32_e32 v2, v2, v55
	s_waitcnt vmcnt(44)
	v_add_f32_e32 v2, v2, v56
	s_waitcnt vmcnt(43)
	v_add_f32_e32 v2, v2, v57
	s_waitcnt vmcnt(42)
	v_add_f32_e32 v2, v2, v58
	s_waitcnt vmcnt(41)
	v_add_f32_e32 v2, v2, v59
	s_waitcnt vmcnt(40)
	v_add_f32_e32 v2, v2, v60
	s_waitcnt vmcnt(39)
	v_add_f32_e32 v2, v2, v61
	s_waitcnt vmcnt(38)
	v_add_f32_e32 v2, v2, v62
	s_waitcnt vmcnt(37)
	v_add_f32_e32 v2, v2, v63
	s_waitcnt vmcnt(36)
	v_add_f32_e32 v2, v2, v64
	s_waitcnt vmcnt(35)
	v_add_f32_e32 v2, v2, v65
	s_waitcnt vmcnt(34)
	v_add_f32_e32 v2, v2, v66
	s_waitcnt vmcnt(33)
	v_add_f32_e32 v2, v2, v67
	s_waitcnt vmcnt(32)
	v_add_f32_e32 v2, v2, v68
	s_waitcnt vmcnt(31)
	v_add_f32_e32 v2, v2, v69
	s_waitcnt vmcnt(30)
	v_add_f32_e32 v2, v2, v70
	s_waitcnt vmcnt(29)
	v_add_f32_e32 v2, v2, v71
	s_waitcnt vmcnt(28)
	v_add_f32_e32 v2, v2, v72
	s_waitcnt vmcnt(27)
	v_add_f32_e32 v2, v2, v73
	s_waitcnt vmcnt(26)
	v_add_f32_e32 v2, v2, v74
	s_waitcnt vmcnt(25)
	v_add_f32_e32 v2, v2, v75
	s_waitcnt vmcnt(24)
	v_add_f32_e32 v2, v2, v76
	s_waitcnt vmcnt(23)
	v_add_f32_e32 v2, v2, v77
	s_waitcnt vmcnt(22)
	v_add_f32_e32 v2, v2, v78
	s_waitcnt vmcnt(21)
	v_add_f32_e32 v2, v2, v79
	s_waitcnt vmcnt(20)
	v_add_f32_e32 v2, v2, v80
	s_waitcnt vmcnt(19)
	v_add_f32_e32 v2, v2, v81
	s_waitcnt vmcnt(18)
	v_add_f32_e32 v2, v2, v82
	s_waitcnt vmcnt(17)
	v_add_f32_e32 v2, v2, v83
	s_waitcnt vmcnt(16)
	v_add_f32_e32 v2, v2, v84
	s_waitcnt vmcnt(15)
	v_add_f32_e32 v2, v2, v85
	s_waitcnt vmcnt(14)
	v_add_f32_e32 v2, v2, v86
	s_waitcnt vmcnt(13)
	v_add_f32_e32 v2, v2, v87
	s_waitcnt vmcnt(12)
	v_add_f32_e32 v2, v2, v88
	s_waitcnt vmcnt(11)
	v_add_f32_e32 v2, v2, v89
	s_waitcnt vmcnt(10)
	v_add_f32_e32 v2, v2, v90
	s_waitcnt vmcnt(9)
	v_add_f32_e32 v2, v2, v91
	s_waitcnt vmcnt(8)
	v_add_f32_e32 v2, v2, v92
	s_waitcnt vmcnt(7)
	v_add_f32_e32 v2, v2, v10
	s_waitcnt vmcnt(6)
	v_add_f32_e32 v2, v2, v93
	s_waitcnt vmcnt(5)
	v_add_f32_e32 v2, v2, v94
	s_waitcnt vmcnt(4)
	v_add_f32_e32 v2, v2, v95
	s_waitcnt vmcnt(3)
	v_add_f32_e32 v2, v2, v96
	s_waitcnt vmcnt(2)
	v_add_f32_e32 v2, v2, v97
	s_waitcnt vmcnt(1)
	v_add_f32_e32 v2, v2, v98
	s_waitcnt vmcnt(0)
	v_add_f32_e32 v2, v2, v99
	ds_write_b32 v12, v2
